# phase 4 rebalance: each SWA+q workgroup keeps one kv-up tile, the other 64 kv-up tiles go to the first 64 NA+q workgroups (NA units are cheaper after the bias-lookup fix)
# baseline (speedup 1.0000x reference)
; __device__ __forceinline__ int opq(int v) { asm volatile("" : "+s"(v)); return v; }
; __global__ void __launch_bounds__(NTHREADS) fwd_megakernel(Args a) {
;     ...
;             { const int bq = opq((int)blockIdx.x), Gq = opq(G);
; #pragma unroll 1
;               for (int it = 0; ; ++it) {
;                 int q0 = -1, kv0 = -1, kv1 = -1, na = -1, sw0 = -1, sw1 = -1;
;                 if (Gq == 256) { if (it == 0) {
;                     if (bq < 96) { na = bq; q0 = bq; }
;                     else if (bq < 128) { na = bq; kv0 = 2 * (bq - 96); kv1 = kv0 + 1; }
;                     else if (bq < 192) { sw0 = bq - 128; q0 = 96 + (bq - 128); kv0 = 64 + 2 * (bq - 128); kv1 = kv0 + 1; }
;                     else { sw0 = 64 + (bq - 192); sw1 = 128 + (bq - 192); } } }
;                 else { const int L = bq + it * Gq; if (L < 160) q0 = L; if (L < 192) { kv0 = L; sw0 = L; } if (L < 128) na = L; }
.LBB0_617:
	s_andn2_b64 vcc, exec, s[0:1]
	s_cbranch_vccnz .LBB0_854
	v_readlane_b32 s0, v254, 46
	v_readlane_b32 s1, v254, 47
	s_mul_i32 s1, s0, 0x5b00000
	s_lshl_b32 s0, s0, 2
	v_writelane_b32 v254, s1, 49
	v_writelane_b32 v254, s0, 50
	v_mov_b32_e32 v0, 0x80
	v_readlane_b32 s0, v254, 11
	s_mov_b32 s5, s0
	s_mov_b32 s0, s82
	v_readlane_b32 s1, v254, 12
	s_cmpk_lg_i32 s0, 0x100
	v_writelane_b32 v254, s0, 51
	s_cselect_b64 s[0:1], -1, 0
	v_writelane_b32 v254, s0, 52
	s_cmpk_gt_i32 s5, 0x5f
	v_sub_co_u32_e32 v0, vcc, s5, v0
	v_writelane_b32 v254, s1, 53
	s_cselect_b64 s[0:1], -1, 0
	v_writelane_b32 v254, s0, 54
	v_readfirstlane_b32 s2, v0
	s_lshl_b32 s4, s5, 1
	v_writelane_b32 v254, s1, 55
	v_readfirstlane_b32 s0, v0
	s_lshl_b32 s2, s2, 1
	s_add_i32 s6, s4, 0xffffff40
	v_writelane_b32 v254, s0, 56
	s_xor_b64 s[0:1], vcc, -1
	v_writelane_b32 v254, s0, 57
	s_add_i32 s3, s2, 64
	s_addk_i32 s2, 0x41
	v_writelane_b32 v254, s1, 58
	s_sub_i32 s0, s5, 64
	s_sub_i32 s1, s5, 32
	v_writelane_b32 v254, s6, 59
	s_addk_i32 s4, 0xff41
	v_writelane_b32 v254, s4, 60
	s_cmpk_lt_u32 s5, 0xc0
	v_writelane_b32 v254, s5, 61
	s_cselect_b32 s0, -1, s0
	v_writelane_b32 v254, s0, 62
	s_mov_b32 s0, -1
	v_writelane_b32 v254, s0, 63
	s_cselect_b32 s0, s3, -1
	v_writelane_b32 v255, s0, 0
	s_cselect_b32 s0, s1, -1
	v_writelane_b32 v255, s0, 1
	s_mov_b32 s0, 0
	v_writelane_b32 v255, s0, 2
	s_branch .LBB0_620

; __global__ void __launch_bounds__(NTHREADS) fwd_megakernel(Args a) {
;     ...
;                 if (Gq == 256) { if (it == 0) {
;                     if (bq < 96) { na = bq; q0 = bq; }
;                     else if (bq < 128) { na = bq; kv0 = 2 * (bq - 96); kv1 = kv0 + 1; }
;                     else if (bq < 192) { sw0 = bq - 128; q0 = 96 + (bq - 128); kv0 = 64 + 2 * (bq - 128); kv1 = kv0 + 1; }
;                     else { sw0 = 64 + (bq - 192); sw1 = 128 + (bq - 192); } } }
;                 else { const int L = bq + it * Gq; if (L < 160) q0 = L; if (L < 192) { kv0 = L; sw0 = L; } if (L < 128) na = L; }
.LBB0_622:
	s_mov_b32 s58, -1
	s_andn2_b64 vcc, exec, s[0:1]
	s_mov_b32 s26, -1
	s_mov_b32 s16, s57
	s_cbranch_vccnz .LBB0_627
	v_readlane_b32 s0, v255, 2
	s_mov_b32 s4, -1
	s_cmp_lg_u32 s0, 0
	s_mov_b32 s16, -1
	s_mov_b32 s30, -1
	s_mov_b32 s57, -1
	s_cbranch_scc1 .LBB0_627
	v_readlane_b32 s0, v254, 54
	v_readlane_b32 s1, v254, 55
	v_readlane_b32 s30, v254, 61
	s_andn2_b64 vcc, exec, s[0:1]
	s_mov_b32 s4, s30
	s_lshl_b32 s16, s30, 1
	s_add_i32 s16, s16, 0x41
	s_cmp_lt_u32 s30, 64
	s_cselect_b32 s16, s16, -1
	s_cbranch_vccnz .LBB0_627
	v_readlane_b32 s0, v254, 57
	v_readlane_b32 s1, v254, 58
	s_mov_b32 s4, -1
	s_andn2_b64 vcc, exec, s[0:1]
	v_readlane_b32 s16, v254, 59
	v_readlane_b32 s26, v254, 60
	v_readlane_b32 s30, v254, 61
	s_cbranch_vccnz .LBB0_627
	s_mov_b32 s30, -1
	v_readlane_b32 s4, v255, 1
	v_readlane_b32 s16, v255, 0
	v_readlane_b32 s26, v254, 63
	v_readlane_b32 s57, v254, 56
	v_readlane_b32 s58, v254, 62
